# P0 rmsnorm trips rebalanced: every workgroup carries 22 units (conversion items + row-group trips)
# baseline (speedup 1.0000x reference)
.LBB0_47:
	v_lshl_add_u64 v[22:23], v[82:83], 4, s[18:19]
	global_load_dwordx4 v[78:81], v[22:23], off
	global_load_dwordx4 v[74:77], v[22:23], off offset:1024
	global_load_dwordx4 v[62:65], v[22:23], off offset:3072
	global_load_dwordx4 v[70:73], v[22:23], off offset:2048
	s_mov_b64 s[18:19], 0x1000
	v_lshl_add_u64 v[2:3], v[22:23], 0, s[18:19]
	global_load_dwordx4 v[54:57], v[2:3], off offset:1024
	global_load_dwordx4 v[50:53], v[2:3], off offset:2048
	global_load_dwordx4 v[46:49], v[2:3], off offset:3072
	v_add_co_u32_e32 v2, vcc, 0x1000, v22
	s_lshl_b64 s[0:1], s[0:1], 11
	s_nop 0
	v_addc_co_u32_e32 v3, vcc, 0, v23, vcc
	global_load_dwordx4 v[66:69], v[2:3], off
	global_load_dwordx4 v[14:17], v[86:87], off
	global_load_dwordx4 v[10:13], v[86:87], off offset:1024
	global_load_dwordx4 v[6:9], v[86:87], off offset:2048
	s_nop 0
	global_load_dwordx4 v[2:5], v[86:87], off offset:3072
	s_mov_b64 s[18:19], 0x2000
	v_add_co_u32_e32 v32, vcc, 0x2000, v22
	v_lshl_add_u64 v[24:25], v[22:23], 0, s[18:19]
	s_mov_b64 s[18:19], 0x3000
	v_lshl_add_u64 v[90:91], v[84:85], 0, s[0:1]
	s_mov_b64 s[0:1], vcc
	v_add_co_u32_e32 v98, vcc, 0x3000, v22
	v_lshl_add_u64 v[30:31], v[22:23], 0, s[18:19]
	v_addc_co_u32_e64 v33, s[0:1], 0, v23, s[0:1]
	v_addc_co_u32_e32 v99, vcc, 0, v23, vcc
	global_load_dwordx4 v[42:45], v[24:25], off offset:1024
	global_load_dwordx4 v[34:37], v[24:25], off offset:2048
	global_load_dwordx4 v[26:29], v[30:31], off offset:1024
	global_load_dwordx4 v[18:21], v[30:31], off offset:2048
	global_load_dwordx4 v[38:41], v[24:25], off offset:3072
	global_load_dwordx4 v[58:61], v[32:33], off
	s_nop 0
	global_load_dwordx4 v[22:25], v[30:31], off offset:3072
	s_nop 0
	global_load_dwordx4 v[30:33], v[98:99], off
	s_movk_i32 s0, 0xf000
	s_add_u32 s16, s16, s8
	s_addc_u32 s17, s17, s9
	s_add_u32 s10, s10, s12
	s_addc_u32 s11, s11, s13
	s_add_i32 s98, s98, 1
	s_cmp_lg_u32 s98, 1
	s_cbranch_scc1 .Lp0_t2
	s_cmpk_ge_u32 s99, 0x580
	s_cbranch_scc1 .Lp0_a
	s_and_b32 s100, s99, 3
	s_cmp_lg_u32 s100, 3
	s_cbranch_scc1 .Lp0_a
	s_movk_i32 s16, 0x7fff
	s_branch .Lp0_a
.Lp0_t2:
	s_cmp_lg_u32 s98, 2
	s_cbranch_scc0 .Lp0_t2b
	s_movk_i32 s16, 0x7fff
	s_branch .Lp0_a
.Lp0_t2b:
	s_movk_i32 s16, 0x7fff
	s_cmpk_lt_u32 s99, 0x580
	s_cbranch_scc1 .Lp0_a
	s_sub_i32 s100, s99, 0x580
	s_and_b32 s101, s100, 7
	s_cmp_ge_u32 s101, 6
	s_cbranch_scc1 .Lp0_a
	s_lshr_b32 s100, s100, 3
	s_mul_i32 s100, s100, 6
	s_add_i32 s100, s100, s101
	s_cmpk_ge_u32 s100, 0x160
	s_cbranch_scc1 .Lp0_s
	s_lshr_b32 s101, s100, 1
	s_lshl_b32 s101, s101, 3
	s_and_b32 s100, s100, 1
	s_lshl_b32 s100, s100, 2
	s_add_i32 s101, s101, s100
	s_add_i32 s101, s101, 3
	s_lshl_b32 s16, s101, 2
	s_add_i32 s16, s16, 0x2000
	s_branch .Lp0_fix
.Lp0_s:
	s_sub_i32 s100, s100, 0x160
	s_lshl_b32 s16, s100, 2
	s_add_i32 s16, s16, 0x4000
.Lp0_fix:
	s_lshl_b32 s100, s99, 2
	s_add_i32 s100, s100, 0x4000
	s_sub_i32 s100, s16, s100
	s_lshl_b32 s101, s100, 12
	s_add_u32 s10, s10, s101
	s_addc_u32 s11, s11, -1
	s_lshl_b32 s101, s100, 11
	s_add_u32 s14, s14, s101
	s_addc_u32 s15, s15, -1
